# A/B deletion of the per-phase s_setprio flips in both GEMM K-loops (step b of the static-priority lever)
# speedup vs baseline: 1.0016x; 1.0016x over previous
.LBB0_149:
	ds_read_b128 v[128:131], v164
	ds_read_b128 v[150:153], v164 offset:1024
	ds_read_b128 v[154:157], v164 offset:2048
	ds_read_b128 v[158:161], v164 offset:3072
	ds_read_b128 v[170:173], v165
	ds_read_b128 v[174:177], v165 offset:1024
	ds_read_b128 v[178:181], v165 offset:2048
	ds_read_b128 v[182:185], v165 offset:3072
	s_add_u32 s17, s42, 0xfff80080
	s_addc_u32 s19, s43, -1
	s_cmp_eq_u32 s16, 28
	s_cselect_b32 s77, s0, s19
	s_cselect_b32 s76, s1, s17
	s_cselect_b32 s75, s12, s15
	s_cselect_b32 s74, s13, s14
	v_lshl_add_u64 v[218:219], s[42:43], 0, v[142:143]
	s_add_i32 m0, s84, 0xc000
	ds_read_b128 v[186:189], v166
	ds_read_b128 v[190:193], v166 offset:1024
	ds_read_b128 v[194:197], v166 offset:2048
	ds_read_b128 v[198:201], v166 offset:3072
	ds_read_b128 v[202:205], v166 offset:4096
	ds_read_b128 v[206:209], v166 offset:5120
	ds_read_b128 v[210:213], v166 offset:6144
	ds_read_b128 v[214:217], v166 offset:7168
	global_load_lds_dwordx4 v[218:219], off
	v_lshl_add_u64 v[218:219], s[42:43], 0, v[144:145]
	s_add_i32 m0, s84, 0xe000
	s_nop 0
	global_load_lds_dwordx4 v[218:219], off
	s_waitcnt vmcnt(8)
	s_waitcnt lgkmcnt(0)
	s_barrier
	s_waitcnt lgkmcnt(0)
	v_mfma_f32_16x16x32_bf16 v[124:127], v[128:131], v[186:189], v[124:127]
	v_mfma_f32_16x16x32_bf16 v[120:123], v[154:157], v[186:189], v[120:123]
	v_mfma_f32_16x16x32_bf16 v[108:111], v[128:131], v[194:197], v[108:111]
	v_mfma_f32_16x16x32_bf16 v[104:107], v[154:157], v[194:197], v[104:107]
	v_mfma_f32_16x16x32_bf16 v[92:95], v[128:131], v[202:205], v[92:95]
	v_mfma_f32_16x16x32_bf16 v[88:91], v[154:157], v[202:205], v[88:91]
	v_mfma_f32_16x16x32_bf16 v[76:79], v[128:131], v[210:213], v[76:79]
	v_mfma_f32_16x16x32_bf16 v[72:75], v[154:157], v[210:213], v[72:75]
	v_mfma_f32_16x16x32_bf16 v[124:127], v[150:153], v[190:193], v[124:127]
	v_mfma_f32_16x16x32_bf16 v[120:123], v[158:161], v[190:193], v[120:123]
	v_mfma_f32_16x16x32_bf16 v[108:111], v[150:153], v[198:201], v[108:111]
	v_mfma_f32_16x16x32_bf16 v[104:107], v[158:161], v[198:201], v[104:107]
	v_mfma_f32_16x16x32_bf16 v[92:95], v[150:153], v[206:209], v[92:95]
	v_mfma_f32_16x16x32_bf16 v[88:91], v[158:161], v[206:209], v[88:91]
	v_mfma_f32_16x16x32_bf16 v[76:79], v[150:153], v[214:217], v[76:79]
	v_mfma_f32_16x16x32_bf16 v[72:75], v[158:161], v[214:217], v[72:75]
	v_mfma_f32_16x16x32_bf16 v[116:119], v[170:173], v[186:189], v[116:119]
	v_mfma_f32_16x16x32_bf16 v[112:115], v[178:181], v[186:189], v[112:115]
	v_mfma_f32_16x16x32_bf16 v[100:103], v[170:173], v[194:197], v[100:103]
	v_mfma_f32_16x16x32_bf16 v[96:99], v[178:181], v[194:197], v[96:99]
	v_mfma_f32_16x16x32_bf16 v[84:87], v[170:173], v[202:205], v[84:87]
	v_mfma_f32_16x16x32_bf16 v[80:83], v[178:181], v[202:205], v[80:83]
	v_mfma_f32_16x16x32_bf16 v[68:71], v[170:173], v[210:213], v[68:71]
	v_mfma_f32_16x16x32_bf16 v[64:67], v[178:181], v[210:213], v[64:67]
	v_mfma_f32_16x16x32_bf16 v[116:119], v[174:177], v[190:193], v[116:119]
	v_mfma_f32_16x16x32_bf16 v[112:115], v[182:185], v[190:193], v[112:115]
	v_mfma_f32_16x16x32_bf16 v[100:103], v[174:177], v[198:201], v[100:103]
	v_mfma_f32_16x16x32_bf16 v[96:99], v[182:185], v[198:201], v[96:99]
	v_mfma_f32_16x16x32_bf16 v[84:87], v[174:177], v[206:209], v[84:87]
	v_mfma_f32_16x16x32_bf16 v[80:83], v[182:185], v[206:209], v[80:83]
	v_mfma_f32_16x16x32_bf16 v[68:71], v[174:177], v[214:217], v[68:71]
	v_mfma_f32_16x16x32_bf16 v[64:67], v[182:185], v[214:217], v[64:67]
	s_barrier
	s_add_i32 s17, s93, s83
	v_lshl_add_u64 v[218:219], s[74:75], 0, v[134:135]
	s_mov_b32 m0, s17
	ds_read_b128 v[186:189], v166 offset:16384
	ds_read_b128 v[190:193], v166 offset:17408
	ds_read_b128 v[194:197], v166 offset:18432
	ds_read_b128 v[198:201], v166 offset:19456
	ds_read_b128 v[202:205], v166 offset:20480
	ds_read_b128 v[206:209], v166 offset:21504
	ds_read_b128 v[210:213], v166 offset:22528
	ds_read_b128 v[214:217], v166 offset:23552
	global_load_lds_dwordx4 v[218:219], off
	s_add_i32 m0, s17, 0x2000
	s_add_u32 s20, s74, 0x80000
	v_lshl_add_u64 v[220:221], s[74:75], 0, v[138:139]
	s_addc_u32 s21, s75, 0
	s_add_i32 s17, s94, s83
	global_load_lds_dwordx4 v[220:221], off
	v_lshl_add_u64 v[222:223], s[20:21], 0, v[134:135]
	s_mov_b32 m0, s17
	v_lshl_add_u64 v[224:225], s[76:77], 0, v[136:137]
	global_load_lds_dwordx4 v[222:223], off
	v_lshl_add_u64 v[222:223], s[20:21], 0, v[138:139]
	s_add_i32 m0, s17, 0x2000
	s_nop 0
	global_load_lds_dwordx4 v[222:223], off
	v_lshl_add_u64 v[222:223], s[76:77], 0, v[132:133]
	s_mov_b32 m0, s84
	s_nop 0
	global_load_lds_dwordx4 v[222:223], off
	s_mov_b32 m0, s85
	s_nop 0
	global_load_lds_dwordx4 v[224:225], off
	s_waitcnt vmcnt(8)
	s_waitcnt lgkmcnt(0)
	s_barrier
	s_waitcnt lgkmcnt(0)
	v_mfma_f32_16x16x32_bf16 v[60:63], v[128:131], v[186:189], v[60:63]
	v_mfma_f32_16x16x32_bf16 v[56:59], v[154:157], v[186:189], v[56:59]
	v_mfma_f32_16x16x32_bf16 v[44:47], v[128:131], v[194:197], v[44:47]
	v_mfma_f32_16x16x32_bf16 v[40:43], v[154:157], v[194:197], v[40:43]
	v_mfma_f32_16x16x32_bf16 v[28:31], v[128:131], v[202:205], v[28:31]
	v_mfma_f32_16x16x32_bf16 v[24:27], v[154:157], v[202:205], v[24:27]
	v_mfma_f32_16x16x32_bf16 v[12:15], v[128:131], v[210:213], v[12:15]
	v_mfma_f32_16x16x32_bf16 v[8:11], v[154:157], v[210:213], v[8:11]
	v_mfma_f32_16x16x32_bf16 v[60:63], v[150:153], v[190:193], v[60:63]
	v_mfma_f32_16x16x32_bf16 v[56:59], v[158:161], v[190:193], v[56:59]
	v_mfma_f32_16x16x32_bf16 v[44:47], v[150:153], v[198:201], v[44:47]
	v_mfma_f32_16x16x32_bf16 v[40:43], v[158:161], v[198:201], v[40:43]
	v_mfma_f32_16x16x32_bf16 v[28:31], v[150:153], v[206:209], v[28:31]
	v_mfma_f32_16x16x32_bf16 v[24:27], v[158:161], v[206:209], v[24:27]
	v_mfma_f32_16x16x32_bf16 v[12:15], v[150:153], v[214:217], v[12:15]
	v_mfma_f32_16x16x32_bf16 v[8:11], v[158:161], v[214:217], v[8:11]
	v_mfma_f32_16x16x32_bf16 v[52:55], v[170:173], v[186:189], v[52:55]
	v_mfma_f32_16x16x32_bf16 v[48:51], v[178:181], v[186:189], v[48:51]
	v_mfma_f32_16x16x32_bf16 v[36:39], v[170:173], v[194:197], v[36:39]
	v_mfma_f32_16x16x32_bf16 v[32:35], v[178:181], v[194:197], v[32:35]
	v_mfma_f32_16x16x32_bf16 v[20:23], v[170:173], v[202:205], v[20:23]
	v_mfma_f32_16x16x32_bf16 v[16:19], v[178:181], v[202:205], v[16:19]
	v_mfma_f32_16x16x32_bf16 v[4:7], v[170:173], v[210:213], v[4:7]
	v_mfma_f32_16x16x32_bf16 v[0:3], v[178:181], v[210:213], v[0:3]
	v_mfma_f32_16x16x32_bf16 v[52:55], v[174:177], v[190:193], v[52:55]
	v_mfma_f32_16x16x32_bf16 v[48:51], v[182:185], v[190:193], v[48:51]
	v_mfma_f32_16x16x32_bf16 v[36:39], v[174:177], v[198:201], v[36:39]
	v_mfma_f32_16x16x32_bf16 v[32:35], v[182:185], v[198:201], v[32:35]
	v_mfma_f32_16x16x32_bf16 v[20:23], v[174:177], v[206:209], v[20:23]
	v_mfma_f32_16x16x32_bf16 v[16:19], v[182:185], v[206:209], v[16:19]
	v_mfma_f32_16x16x32_bf16 v[4:7], v[174:177], v[214:217], v[4:7]
	v_mfma_f32_16x16x32_bf16 v[0:3], v[182:185], v[214:217], v[0:3]
	s_barrier
	s_add_i32 s17, 0, 0x18000
	v_add_u32_e32 v140, s17, v162
	s_add_i32 s19, 0, 0x1c000
	ds_read_b128 v[128:131], v140
	ds_read_b128 v[150:153], v140 offset:1024
	ds_read_b128 v[154:157], v140 offset:2048
	ds_read_b128 v[158:161], v140 offset:3072
	v_add_u32_e32 v140, s19, v162
	ds_read_b128 v[170:173], v140
	ds_read_b128 v[174:177], v140 offset:1024
	ds_read_b128 v[178:181], v140 offset:2048
	ds_read_b128 v[182:185], v140 offset:3072
	s_add_u32 s20, s76, 0x80000
	s_addc_u32 s21, s77, 0
	s_mov_b32 m0, s86
	v_lshl_add_u64 v[226:227], s[20:21], 0, v[132:133]
	ds_read_b128 v[186:189], v166 offset:32768
	ds_read_b128 v[190:193], v166 offset:33792
	ds_read_b128 v[194:197], v166 offset:34816
	ds_read_b128 v[198:201], v166 offset:35840
	ds_read_b128 v[202:205], v166 offset:36864
	ds_read_b128 v[206:209], v166 offset:37888
	ds_read_b128 v[210:213], v166 offset:38912
	ds_read_b128 v[214:217], v166 offset:39936
	global_load_lds_dwordx4 v[226:227], off
	v_lshl_add_u64 v[226:227], s[20:21], 0, v[136:137]
	s_mov_b32 m0, s87
	s_nop 0
	global_load_lds_dwordx4 v[226:227], off
	s_waitcnt vmcnt(8)
	s_waitcnt lgkmcnt(0)
	s_barrier
	s_waitcnt lgkmcnt(0)
	v_mfma_f32_16x16x32_bf16 v[124:127], v[128:131], v[186:189], v[124:127]
	v_mfma_f32_16x16x32_bf16 v[120:123], v[154:157], v[186:189], v[120:123]
	v_mfma_f32_16x16x32_bf16 v[108:111], v[128:131], v[194:197], v[108:111]
	v_mfma_f32_16x16x32_bf16 v[104:107], v[154:157], v[194:197], v[104:107]
	v_mfma_f32_16x16x32_bf16 v[92:95], v[128:131], v[202:205], v[92:95]
	v_mfma_f32_16x16x32_bf16 v[88:91], v[154:157], v[202:205], v[88:91]
	v_mfma_f32_16x16x32_bf16 v[76:79], v[128:131], v[210:213], v[76:79]
	v_mfma_f32_16x16x32_bf16 v[72:75], v[154:157], v[210:213], v[72:75]
	v_mfma_f32_16x16x32_bf16 v[124:127], v[150:153], v[190:193], v[124:127]
	v_mfma_f32_16x16x32_bf16 v[120:123], v[158:161], v[190:193], v[120:123]
	v_mfma_f32_16x16x32_bf16 v[108:111], v[150:153], v[198:201], v[108:111]
	v_mfma_f32_16x16x32_bf16 v[104:107], v[158:161], v[198:201], v[104:107]
	v_mfma_f32_16x16x32_bf16 v[92:95], v[150:153], v[206:209], v[92:95]
	v_mfma_f32_16x16x32_bf16 v[88:91], v[158:161], v[206:209], v[88:91]
	v_mfma_f32_16x16x32_bf16 v[76:79], v[150:153], v[214:217], v[76:79]
	v_mfma_f32_16x16x32_bf16 v[72:75], v[158:161], v[214:217], v[72:75]
	v_mfma_f32_16x16x32_bf16 v[116:119], v[170:173], v[186:189], v[116:119]
	v_mfma_f32_16x16x32_bf16 v[112:115], v[178:181], v[186:189], v[112:115]
	v_mfma_f32_16x16x32_bf16 v[100:103], v[170:173], v[194:197], v[100:103]
	v_mfma_f32_16x16x32_bf16 v[96:99], v[178:181], v[194:197], v[96:99]
	v_mfma_f32_16x16x32_bf16 v[84:87], v[170:173], v[202:205], v[84:87]
	v_mfma_f32_16x16x32_bf16 v[80:83], v[178:181], v[202:205], v[80:83]
	v_mfma_f32_16x16x32_bf16 v[68:71], v[170:173], v[210:213], v[68:71]
	v_mfma_f32_16x16x32_bf16 v[64:67], v[178:181], v[210:213], v[64:67]
	v_mfma_f32_16x16x32_bf16 v[116:119], v[174:177], v[190:193], v[116:119]
	v_mfma_f32_16x16x32_bf16 v[112:115], v[182:185], v[190:193], v[112:115]
	v_mfma_f32_16x16x32_bf16 v[100:103], v[174:177], v[198:201], v[100:103]
	v_mfma_f32_16x16x32_bf16 v[96:99], v[182:185], v[198:201], v[96:99]
	v_mfma_f32_16x16x32_bf16 v[84:87], v[174:177], v[206:209], v[84:87]
	v_mfma_f32_16x16x32_bf16 v[80:83], v[182:185], v[206:209], v[80:83]
	v_mfma_f32_16x16x32_bf16 v[68:71], v[174:177], v[214:217], v[68:71]
	v_mfma_f32_16x16x32_bf16 v[64:67], v[182:185], v[214:217], v[64:67]
	s_barrier
	s_add_i32 s17, s17, s83
	v_lshl_add_u64 v[218:219], v[218:219], 0, s[10:11]
	s_mov_b32 m0, s17
	ds_read_b128 v[186:189], v166 offset:49152
	ds_read_b128 v[190:193], v166 offset:50176
	ds_read_b128 v[194:197], v166 offset:51200
	ds_read_b128 v[198:201], v166 offset:52224
	ds_read_b128 v[202:205], v166 offset:53248
	ds_read_b128 v[206:209], v166 offset:54272
	ds_read_b128 v[210:213], v166 offset:55296
	ds_read_b128 v[214:217], v166 offset:56320
	global_load_lds_dwordx4 v[218:219], off
	s_add_i32 m0, s17, 0x2000
	s_add_u32 s20, s74, 0x80080
	v_lshl_add_u64 v[218:219], v[220:221], 0, s[10:11]
	s_addc_u32 s21, s75, 0
	s_add_i32 s17, s19, s83
	global_load_lds_dwordx4 v[218:219], off
	v_lshl_add_u64 v[218:219], s[20:21], 0, v[134:135]
	s_mov_b32 m0, s17
	s_nop 0
	global_load_lds_dwordx4 v[218:219], off
	v_lshl_add_u64 v[218:219], s[20:21], 0, v[138:139]
	s_add_i32 m0, s17, 0x2000
	s_nop 0
	global_load_lds_dwordx4 v[218:219], off
	v_lshl_add_u64 v[218:219], v[222:223], 0, s[10:11]
	s_mov_b32 m0, s91
	s_nop 0
	global_load_lds_dwordx4 v[218:219], off
	v_lshl_add_u64 v[218:219], v[224:225], 0, s[10:11]
	s_mov_b32 m0, s92
	s_nop 0
	global_load_lds_dwordx4 v[218:219], off
	s_waitcnt vmcnt(8)
	s_waitcnt lgkmcnt(0)
	s_barrier
	s_waitcnt lgkmcnt(0)
	v_mfma_f32_16x16x32_bf16 v[60:63], v[128:131], v[186:189], v[60:63]
	v_mfma_f32_16x16x32_bf16 v[56:59], v[154:157], v[186:189], v[56:59]
	v_mfma_f32_16x16x32_bf16 v[44:47], v[128:131], v[194:197], v[44:47]
	v_mfma_f32_16x16x32_bf16 v[40:43], v[154:157], v[194:197], v[40:43]
	v_mfma_f32_16x16x32_bf16 v[28:31], v[128:131], v[202:205], v[28:31]
	v_mfma_f32_16x16x32_bf16 v[24:27], v[154:157], v[202:205], v[24:27]
	v_mfma_f32_16x16x32_bf16 v[12:15], v[128:131], v[210:213], v[12:15]
	v_mfma_f32_16x16x32_bf16 v[8:11], v[154:157], v[210:213], v[8:11]
	v_mfma_f32_16x16x32_bf16 v[60:63], v[150:153], v[190:193], v[60:63]
	v_mfma_f32_16x16x32_bf16 v[56:59], v[158:161], v[190:193], v[56:59]
	v_mfma_f32_16x16x32_bf16 v[44:47], v[150:153], v[198:201], v[44:47]
	v_mfma_f32_16x16x32_bf16 v[40:43], v[158:161], v[198:201], v[40:43]
	v_mfma_f32_16x16x32_bf16 v[28:31], v[150:153], v[206:209], v[28:31]
	v_mfma_f32_16x16x32_bf16 v[24:27], v[158:161], v[206:209], v[24:27]
	v_mfma_f32_16x16x32_bf16 v[12:15], v[150:153], v[214:217], v[12:15]
	v_mfma_f32_16x16x32_bf16 v[8:11], v[158:161], v[214:217], v[8:11]
	v_mfma_f32_16x16x32_bf16 v[52:55], v[170:173], v[186:189], v[52:55]
	v_mfma_f32_16x16x32_bf16 v[48:51], v[178:181], v[186:189], v[48:51]
	v_mfma_f32_16x16x32_bf16 v[36:39], v[170:173], v[194:197], v[36:39]
	v_mfma_f32_16x16x32_bf16 v[32:35], v[178:181], v[194:197], v[32:35]
	v_mfma_f32_16x16x32_bf16 v[20:23], v[170:173], v[202:205], v[20:23]
	v_mfma_f32_16x16x32_bf16 v[16:19], v[178:181], v[202:205], v[16:19]
	v_mfma_f32_16x16x32_bf16 v[4:7], v[170:173], v[210:213], v[4:7]
	v_mfma_f32_16x16x32_bf16 v[0:3], v[178:181], v[210:213], v[0:3]
	v_mfma_f32_16x16x32_bf16 v[52:55], v[174:177], v[190:193], v[52:55]
	v_mfma_f32_16x16x32_bf16 v[48:51], v[182:185], v[190:193], v[48:51]
	v_mfma_f32_16x16x32_bf16 v[36:39], v[174:177], v[198:201], v[36:39]
	v_mfma_f32_16x16x32_bf16 v[32:35], v[182:185], v[198:201], v[32:35]
	v_mfma_f32_16x16x32_bf16 v[20:23], v[174:177], v[206:209], v[20:23]
	v_mfma_f32_16x16x32_bf16 v[16:19], v[182:185], v[206:209], v[16:19]
	v_mfma_f32_16x16x32_bf16 v[4:7], v[174:177], v[214:217], v[4:7]
	v_mfma_f32_16x16x32_bf16 v[0:3], v[182:185], v[214:217], v[0:3]
	s_barrier
	s_add_i32 s16, s16, 2
	s_add_u32 s42, s42, 0x100
	s_addc_u32 s43, s43, 0
	s_add_u32 s14, s14, 0x100
	s_addc_u32 s15, s15, 0
	s_cmp_gt_u32 s16, 29
	s_cbranch_scc0 .LBB0_149
	s_and_b64 vcc, exec, s[30:31]
	s_cbranch_vccz .LBB0_152
	s_barrier

.LBB0_661:
	v_add_u32_e32 v149, s42, v147
	ds_read_b128 v[150:153], v149
	ds_read_b128 v[154:157], v149 offset:1024
	ds_read_b128 v[158:161], v149 offset:2048
	ds_read_b128 v[162:165], v149 offset:3072
	v_add_u32_e32 v149, s43, v147
	s_add_u32 s24, s10, s22
	ds_read_b128 v[170:173], v149
	ds_read_b128 v[174:177], v149 offset:1024
	ds_read_b128 v[178:181], v149 offset:2048
	ds_read_b128 v[182:185], v149 offset:3072
	s_addc_u32 s25, s11, s23
	s_add_u32 s24, s24, 0x100
	s_addc_u32 s25, s25, 0
	s_add_u32 s52, s47, s22
	s_addc_u32 s53, s48, s23
	s_cmpk_eq_i32 s22, 0xf00
	s_cselect_b32 s27, s17, s25
	s_cselect_b32 s26, s49, s24
	s_cselect_b32 s25, s15, s53
	s_cselect_b32 s24, s50, s52
	v_lshl_add_u64 v[166:167], v[140:141], 0, s[22:23]
	s_add_i32 m0, s29, 0xc000
	ds_read_b128 v[186:189], v148
	ds_read_b128 v[190:193], v148 offset:1024
	ds_read_b128 v[194:197], v148 offset:2048
	ds_read_b128 v[198:201], v148 offset:3072
	ds_read_b128 v[202:205], v148 offset:4096
	ds_read_b128 v[206:209], v148 offset:5120
	ds_read_b128 v[210:213], v148 offset:6144
	ds_read_b128 v[214:217], v148 offset:7168
	global_load_lds_dwordx4 v[166:167], off
	v_lshl_add_u64 v[166:167], v[142:143], 0, s[22:23]
	s_add_i32 m0, s29, 0xe000
	s_nop 0
	global_load_lds_dwordx4 v[166:167], off
	s_waitcnt vmcnt(8)
	s_waitcnt lgkmcnt(0)
	s_barrier
	s_waitcnt lgkmcnt(0)
	v_mfma_f32_16x16x32_bf16 v[124:127], v[150:153], v[186:189], v[124:127]
	v_mfma_f32_16x16x32_bf16 v[120:123], v[158:161], v[186:189], v[120:123]
	v_mfma_f32_16x16x32_bf16 v[108:111], v[150:153], v[194:197], v[108:111]
	v_mfma_f32_16x16x32_bf16 v[104:107], v[158:161], v[194:197], v[104:107]
	v_mfma_f32_16x16x32_bf16 v[92:95], v[150:153], v[202:205], v[92:95]
	v_mfma_f32_16x16x32_bf16 v[88:91], v[158:161], v[202:205], v[88:91]
	v_mfma_f32_16x16x32_bf16 v[76:79], v[150:153], v[210:213], v[76:79]
	v_mfma_f32_16x16x32_bf16 v[72:75], v[158:161], v[210:213], v[72:75]
	v_mfma_f32_16x16x32_bf16 v[124:127], v[154:157], v[190:193], v[124:127]
	v_mfma_f32_16x16x32_bf16 v[120:123], v[162:165], v[190:193], v[120:123]
	v_mfma_f32_16x16x32_bf16 v[108:111], v[154:157], v[198:201], v[108:111]
	v_mfma_f32_16x16x32_bf16 v[104:107], v[162:165], v[198:201], v[104:107]
	v_mfma_f32_16x16x32_bf16 v[92:95], v[154:157], v[206:209], v[92:95]
	v_mfma_f32_16x16x32_bf16 v[88:91], v[162:165], v[206:209], v[88:91]
	v_mfma_f32_16x16x32_bf16 v[76:79], v[154:157], v[214:217], v[76:79]
	v_mfma_f32_16x16x32_bf16 v[72:75], v[162:165], v[214:217], v[72:75]
	v_mfma_f32_16x16x32_bf16 v[116:119], v[170:173], v[186:189], v[116:119]
	v_mfma_f32_16x16x32_bf16 v[112:115], v[178:181], v[186:189], v[112:115]
	v_mfma_f32_16x16x32_bf16 v[100:103], v[170:173], v[194:197], v[100:103]
	v_mfma_f32_16x16x32_bf16 v[96:99], v[178:181], v[194:197], v[96:99]
	v_mfma_f32_16x16x32_bf16 v[84:87], v[170:173], v[202:205], v[84:87]
	v_mfma_f32_16x16x32_bf16 v[80:83], v[178:181], v[202:205], v[80:83]
	v_mfma_f32_16x16x32_bf16 v[68:71], v[170:173], v[210:213], v[68:71]
	v_mfma_f32_16x16x32_bf16 v[64:67], v[178:181], v[210:213], v[64:67]
	v_mfma_f32_16x16x32_bf16 v[116:119], v[174:177], v[190:193], v[116:119]
	v_mfma_f32_16x16x32_bf16 v[112:115], v[182:185], v[190:193], v[112:115]
	v_mfma_f32_16x16x32_bf16 v[100:103], v[174:177], v[198:201], v[100:103]
	v_mfma_f32_16x16x32_bf16 v[96:99], v[182:185], v[198:201], v[96:99]
	v_mfma_f32_16x16x32_bf16 v[84:87], v[174:177], v[206:209], v[84:87]
	v_mfma_f32_16x16x32_bf16 v[80:83], v[182:185], v[206:209], v[80:83]
	v_mfma_f32_16x16x32_bf16 v[68:71], v[174:177], v[214:217], v[68:71]
	v_mfma_f32_16x16x32_bf16 v[64:67], v[182:185], v[214:217], v[64:67]
	s_barrier
	s_add_i32 s52, s42, s9
	v_lshl_add_u64 v[166:167], s[24:25], 0, v[130:131]
	s_mov_b32 m0, s52
	ds_read_b128 v[186:189], v148 offset:16384
	ds_read_b128 v[190:193], v148 offset:17408
	ds_read_b128 v[194:197], v148 offset:18432
	ds_read_b128 v[198:201], v148 offset:19456
	ds_read_b128 v[202:205], v148 offset:20480
	ds_read_b128 v[206:209], v148 offset:21504
	ds_read_b128 v[210:213], v148 offset:22528
	ds_read_b128 v[214:217], v148 offset:23552
	global_load_lds_dwordx4 v[166:167], off
	s_add_i32 m0, s52, 0x2000
	s_add_u32 s52, s24, 0x80000
	v_lshl_add_u64 v[218:219], s[24:25], 0, v[128:129]
	s_addc_u32 s53, s25, 0
	s_add_i32 s54, s43, s9
	global_load_lds_dwordx4 v[218:219], off
	v_lshl_add_u64 v[220:221], s[52:53], 0, v[130:131]
	s_mov_b32 m0, s54
	v_lshl_add_u64 v[222:223], s[26:27], 0, v[128:129]
	global_load_lds_dwordx4 v[220:221], off
	v_lshl_add_u64 v[220:221], s[52:53], 0, v[128:129]
	s_add_i32 m0, s54, 0x2000
	s_nop 0
	global_load_lds_dwordx4 v[220:221], off
	v_lshl_add_u64 v[220:221], s[26:27], 0, v[130:131]
	s_mov_b32 m0, s29
	s_nop 0
	global_load_lds_dwordx4 v[220:221], off
	s_mov_b32 m0, s33
	s_nop 0
	global_load_lds_dwordx4 v[222:223], off
	s_waitcnt vmcnt(8)
	s_waitcnt lgkmcnt(0)
	s_barrier
	s_waitcnt lgkmcnt(0)
	v_mfma_f32_16x16x32_bf16 v[60:63], v[150:153], v[186:189], v[60:63]
	v_mfma_f32_16x16x32_bf16 v[56:59], v[158:161], v[186:189], v[56:59]
	v_mfma_f32_16x16x32_bf16 v[44:47], v[150:153], v[194:197], v[44:47]
	v_mfma_f32_16x16x32_bf16 v[40:43], v[158:161], v[194:197], v[40:43]
	v_mfma_f32_16x16x32_bf16 v[28:31], v[150:153], v[202:205], v[28:31]
	v_mfma_f32_16x16x32_bf16 v[24:27], v[158:161], v[202:205], v[24:27]
	v_mfma_f32_16x16x32_bf16 v[12:15], v[150:153], v[210:213], v[12:15]
	v_mfma_f32_16x16x32_bf16 v[8:11], v[158:161], v[210:213], v[8:11]
	v_mfma_f32_16x16x32_bf16 v[60:63], v[154:157], v[190:193], v[60:63]
	v_mfma_f32_16x16x32_bf16 v[56:59], v[162:165], v[190:193], v[56:59]
	v_mfma_f32_16x16x32_bf16 v[44:47], v[154:157], v[198:201], v[44:47]
	v_mfma_f32_16x16x32_bf16 v[40:43], v[162:165], v[198:201], v[40:43]
	v_mfma_f32_16x16x32_bf16 v[28:31], v[154:157], v[206:209], v[28:31]
	v_mfma_f32_16x16x32_bf16 v[24:27], v[162:165], v[206:209], v[24:27]
	v_mfma_f32_16x16x32_bf16 v[12:15], v[154:157], v[214:217], v[12:15]
	v_mfma_f32_16x16x32_bf16 v[8:11], v[162:165], v[214:217], v[8:11]
	v_mfma_f32_16x16x32_bf16 v[52:55], v[170:173], v[186:189], v[52:55]
	v_mfma_f32_16x16x32_bf16 v[48:51], v[178:181], v[186:189], v[48:51]
	v_mfma_f32_16x16x32_bf16 v[36:39], v[170:173], v[194:197], v[36:39]
	v_mfma_f32_16x16x32_bf16 v[32:35], v[178:181], v[194:197], v[32:35]
	v_mfma_f32_16x16x32_bf16 v[20:23], v[170:173], v[202:205], v[20:23]
	v_mfma_f32_16x16x32_bf16 v[16:19], v[178:181], v[202:205], v[16:19]
	v_mfma_f32_16x16x32_bf16 v[4:7], v[170:173], v[210:213], v[4:7]
	v_mfma_f32_16x16x32_bf16 v[0:3], v[178:181], v[210:213], v[0:3]
	v_mfma_f32_16x16x32_bf16 v[52:55], v[174:177], v[190:193], v[52:55]
	v_mfma_f32_16x16x32_bf16 v[48:51], v[182:185], v[190:193], v[48:51]
	v_mfma_f32_16x16x32_bf16 v[36:39], v[174:177], v[198:201], v[36:39]
	v_mfma_f32_16x16x32_bf16 v[32:35], v[182:185], v[198:201], v[32:35]
	v_mfma_f32_16x16x32_bf16 v[20:23], v[174:177], v[206:209], v[20:23]
	v_mfma_f32_16x16x32_bf16 v[16:19], v[182:185], v[206:209], v[16:19]
	v_mfma_f32_16x16x32_bf16 v[4:7], v[174:177], v[214:217], v[4:7]
	v_mfma_f32_16x16x32_bf16 v[0:3], v[182:185], v[214:217], v[0:3]
	s_barrier
	s_add_i32 s52, 0, 0x18000
	v_add_u32_e32 v149, s52, v147
	s_add_i32 s53, 0, 0x1c000
	ds_read_b128 v[150:153], v149
	ds_read_b128 v[154:157], v149 offset:1024
	ds_read_b128 v[158:161], v149 offset:2048
	ds_read_b128 v[162:165], v149 offset:3072
	v_add_u32_e32 v149, s53, v147
	ds_read_b128 v[170:173], v149
	ds_read_b128 v[174:177], v149 offset:1024
	ds_read_b128 v[178:181], v149 offset:2048
	ds_read_b128 v[182:185], v149 offset:3072
	s_add_u32 s26, s26, 0x80000
	s_addc_u32 s27, s27, 0
	s_mov_b32 m0, s36
	v_lshl_add_u64 v[224:225], s[26:27], 0, v[130:131]
	ds_read_b128 v[186:189], v148 offset:32768
	ds_read_b128 v[190:193], v148 offset:33792
	ds_read_b128 v[194:197], v148 offset:34816
	ds_read_b128 v[198:201], v148 offset:35840
	ds_read_b128 v[202:205], v148 offset:36864
	ds_read_b128 v[206:209], v148 offset:37888
	ds_read_b128 v[210:213], v148 offset:38912
	ds_read_b128 v[214:217], v148 offset:39936
	global_load_lds_dwordx4 v[224:225], off
	v_lshl_add_u64 v[224:225], s[26:27], 0, v[128:129]
	s_mov_b32 m0, s37
	s_nop 0
	global_load_lds_dwordx4 v[224:225], off
	s_waitcnt vmcnt(8)
	s_waitcnt lgkmcnt(0)
	s_barrier
	s_waitcnt lgkmcnt(0)
	v_mfma_f32_16x16x32_bf16 v[124:127], v[150:153], v[186:189], v[124:127]
	v_mfma_f32_16x16x32_bf16 v[120:123], v[158:161], v[186:189], v[120:123]
	v_mfma_f32_16x16x32_bf16 v[108:111], v[150:153], v[194:197], v[108:111]
	v_mfma_f32_16x16x32_bf16 v[104:107], v[158:161], v[194:197], v[104:107]
	v_mfma_f32_16x16x32_bf16 v[92:95], v[150:153], v[202:205], v[92:95]
	v_mfma_f32_16x16x32_bf16 v[88:91], v[158:161], v[202:205], v[88:91]
	v_mfma_f32_16x16x32_bf16 v[76:79], v[150:153], v[210:213], v[76:79]
	v_mfma_f32_16x16x32_bf16 v[72:75], v[158:161], v[210:213], v[72:75]
	v_mfma_f32_16x16x32_bf16 v[124:127], v[154:157], v[190:193], v[124:127]
	v_mfma_f32_16x16x32_bf16 v[120:123], v[162:165], v[190:193], v[120:123]
	v_mfma_f32_16x16x32_bf16 v[108:111], v[154:157], v[198:201], v[108:111]
	v_mfma_f32_16x16x32_bf16 v[104:107], v[162:165], v[198:201], v[104:107]
	v_mfma_f32_16x16x32_bf16 v[92:95], v[154:157], v[206:209], v[92:95]
	v_mfma_f32_16x16x32_bf16 v[88:91], v[162:165], v[206:209], v[88:91]
	v_mfma_f32_16x16x32_bf16 v[76:79], v[154:157], v[214:217], v[76:79]
	v_mfma_f32_16x16x32_bf16 v[72:75], v[162:165], v[214:217], v[72:75]
	v_mfma_f32_16x16x32_bf16 v[116:119], v[170:173], v[186:189], v[116:119]
	v_mfma_f32_16x16x32_bf16 v[112:115], v[178:181], v[186:189], v[112:115]
	v_mfma_f32_16x16x32_bf16 v[100:103], v[170:173], v[194:197], v[100:103]
	v_mfma_f32_16x16x32_bf16 v[96:99], v[178:181], v[194:197], v[96:99]
	v_mfma_f32_16x16x32_bf16 v[84:87], v[170:173], v[202:205], v[84:87]
	v_mfma_f32_16x16x32_bf16 v[80:83], v[178:181], v[202:205], v[80:83]
	v_mfma_f32_16x16x32_bf16 v[68:71], v[170:173], v[210:213], v[68:71]
	v_mfma_f32_16x16x32_bf16 v[64:67], v[178:181], v[210:213], v[64:67]
	v_mfma_f32_16x16x32_bf16 v[116:119], v[174:177], v[190:193], v[116:119]
	v_mfma_f32_16x16x32_bf16 v[112:115], v[182:185], v[190:193], v[112:115]
	v_mfma_f32_16x16x32_bf16 v[100:103], v[174:177], v[198:201], v[100:103]
	v_mfma_f32_16x16x32_bf16 v[96:99], v[182:185], v[198:201], v[96:99]
	v_mfma_f32_16x16x32_bf16 v[84:87], v[174:177], v[206:209], v[84:87]
	v_mfma_f32_16x16x32_bf16 v[80:83], v[182:185], v[206:209], v[80:83]
	v_mfma_f32_16x16x32_bf16 v[68:71], v[174:177], v[214:217], v[68:71]
	v_mfma_f32_16x16x32_bf16 v[64:67], v[182:185], v[214:217], v[64:67]
	s_barrier
	s_add_i32 s26, s52, s9
	v_lshl_add_u64 v[166:167], v[166:167], 0, s[12:13]
	s_mov_b32 m0, s26
	ds_read_b128 v[186:189], v148 offset:49152
	ds_read_b128 v[190:193], v148 offset:50176
	ds_read_b128 v[194:197], v148 offset:51200
	ds_read_b128 v[198:201], v148 offset:52224
	ds_read_b128 v[202:205], v148 offset:53248
	ds_read_b128 v[206:209], v148 offset:54272
	ds_read_b128 v[210:213], v148 offset:55296
	ds_read_b128 v[214:217], v148 offset:56320
	global_load_lds_dwordx4 v[166:167], off
	s_add_i32 m0, s26, 0x2000
	s_add_u32 s24, s24, 0x80080
	v_lshl_add_u64 v[166:167], v[218:219], 0, s[12:13]
	s_addc_u32 s25, s25, 0
	s_add_i32 s26, s53, s9
	global_load_lds_dwordx4 v[166:167], off
	v_lshl_add_u64 v[166:167], s[24:25], 0, v[130:131]
	s_mov_b32 m0, s26
	s_nop 0
	global_load_lds_dwordx4 v[166:167], off
	v_lshl_add_u64 v[166:167], s[24:25], 0, v[128:129]
	s_add_i32 m0, s26, 0x2000
	s_nop 0
	global_load_lds_dwordx4 v[166:167], off
	v_lshl_add_u64 v[166:167], v[220:221], 0, s[12:13]
	s_mov_b32 m0, s39
	s_nop 0
	global_load_lds_dwordx4 v[166:167], off
	v_lshl_add_u64 v[166:167], v[222:223], 0, s[12:13]
	s_mov_b32 m0, s40
	s_nop 0
	global_load_lds_dwordx4 v[166:167], off
	s_waitcnt vmcnt(8)
	s_waitcnt lgkmcnt(0)
	s_barrier
	s_waitcnt lgkmcnt(0)
	v_mfma_f32_16x16x32_bf16 v[60:63], v[150:153], v[186:189], v[60:63]
	v_mfma_f32_16x16x32_bf16 v[56:59], v[158:161], v[186:189], v[56:59]
	v_mfma_f32_16x16x32_bf16 v[44:47], v[150:153], v[194:197], v[44:47]
	v_mfma_f32_16x16x32_bf16 v[40:43], v[158:161], v[194:197], v[40:43]
	v_mfma_f32_16x16x32_bf16 v[28:31], v[150:153], v[202:205], v[28:31]
	v_mfma_f32_16x16x32_bf16 v[24:27], v[158:161], v[202:205], v[24:27]
	v_mfma_f32_16x16x32_bf16 v[12:15], v[150:153], v[210:213], v[12:15]
	v_mfma_f32_16x16x32_bf16 v[8:11], v[158:161], v[210:213], v[8:11]
	v_mfma_f32_16x16x32_bf16 v[60:63], v[154:157], v[190:193], v[60:63]
	v_mfma_f32_16x16x32_bf16 v[56:59], v[162:165], v[190:193], v[56:59]
	v_mfma_f32_16x16x32_bf16 v[44:47], v[154:157], v[198:201], v[44:47]
	v_mfma_f32_16x16x32_bf16 v[40:43], v[162:165], v[198:201], v[40:43]
	v_mfma_f32_16x16x32_bf16 v[28:31], v[154:157], v[206:209], v[28:31]
	v_mfma_f32_16x16x32_bf16 v[24:27], v[162:165], v[206:209], v[24:27]
	v_mfma_f32_16x16x32_bf16 v[12:15], v[154:157], v[214:217], v[12:15]
	v_mfma_f32_16x16x32_bf16 v[8:11], v[162:165], v[214:217], v[8:11]
	v_mfma_f32_16x16x32_bf16 v[52:55], v[170:173], v[186:189], v[52:55]
	v_mfma_f32_16x16x32_bf16 v[48:51], v[178:181], v[186:189], v[48:51]
	v_mfma_f32_16x16x32_bf16 v[36:39], v[170:173], v[194:197], v[36:39]
	v_mfma_f32_16x16x32_bf16 v[32:35], v[178:181], v[194:197], v[32:35]
	v_mfma_f32_16x16x32_bf16 v[20:23], v[170:173], v[202:205], v[20:23]
	v_mfma_f32_16x16x32_bf16 v[16:19], v[178:181], v[202:205], v[16:19]
	v_mfma_f32_16x16x32_bf16 v[4:7], v[170:173], v[210:213], v[4:7]
	v_mfma_f32_16x16x32_bf16 v[0:3], v[178:181], v[210:213], v[0:3]
	v_mfma_f32_16x16x32_bf16 v[52:55], v[174:177], v[190:193], v[52:55]
	v_mfma_f32_16x16x32_bf16 v[48:51], v[182:185], v[190:193], v[48:51]
	v_mfma_f32_16x16x32_bf16 v[36:39], v[174:177], v[198:201], v[36:39]
	v_mfma_f32_16x16x32_bf16 v[32:35], v[182:185], v[198:201], v[32:35]
	v_mfma_f32_16x16x32_bf16 v[20:23], v[174:177], v[206:209], v[20:23]
	v_mfma_f32_16x16x32_bf16 v[16:19], v[182:185], v[206:209], v[16:19]
	v_mfma_f32_16x16x32_bf16 v[4:7], v[174:177], v[214:217], v[4:7]
	v_mfma_f32_16x16x32_bf16 v[0:3], v[182:185], v[214:217], v[0:3]
	s_barrier
	s_add_i32 s51, s51, 2
	s_add_u32 s22, s22, 0x100
	s_addc_u32 s23, s23, 0
	s_cmp_gt_u32 s51, 29
	s_cbranch_scc0 .LBB0_661
	s_add_u32 s22, s47, 0xffffff00
	s_addc_u32 s23, s48, -1
	s_andn2_b64 vcc, exec, s[4:5]
	s_cbranch_vccnz .LBB0_652
	v_mov_b32_e32 v0, 0
	s_mov_b32 s8, s14
	s_mov_b32 s6, s16
	s_mov_b64 s[10:11], s[20:21]
	s_mov_b32 s41, s46
	v_mov_b32_e32 v1, v0
	v_mov_b32_e32 v2, v0
	v_mov_b32_e32 v3, v0
	v_mov_b32_e32 v4, v0
	v_mov_b32_e32 v5, v0
	v_mov_b32_e32 v6, v0
	v_mov_b32_e32 v7, v0
	v_mov_b32_e32 v16, v0
	v_mov_b32_e32 v17, v0
	v_mov_b32_e32 v18, v0
	v_mov_b32_e32 v19, v0
	v_mov_b32_e32 v20, v0
	v_mov_b32_e32 v21, v0
	v_mov_b32_e32 v22, v0
	v_mov_b32_e32 v23, v0
	v_mov_b32_e32 v32, v0
	v_mov_b32_e32 v33, v0
	v_mov_b32_e32 v34, v0
	v_mov_b32_e32 v35, v0
	v_mov_b32_e32 v36, v0
	v_mov_b32_e32 v37, v0
	v_mov_b32_e32 v38, v0
	v_mov_b32_e32 v39, v0
	v_mov_b32_e32 v48, v0
	v_mov_b32_e32 v49, v0
	v_mov_b32_e32 v50, v0
	v_mov_b32_e32 v51, v0
	v_mov_b32_e32 v52, v0
	v_mov_b32_e32 v53, v0
	v_mov_b32_e32 v54, v0
	v_mov_b32_e32 v55, v0
	v_mov_b32_e32 v8, v0
	v_mov_b32_e32 v9, v0
	v_mov_b32_e32 v10, v0
	v_mov_b32_e32 v11, v0
	v_mov_b32_e32 v12, v0
	v_mov_b32_e32 v13, v0
	v_mov_b32_e32 v14, v0
	v_mov_b32_e32 v15, v0
	v_mov_b32_e32 v24, v0
	v_mov_b32_e32 v25, v0
	v_mov_b32_e32 v26, v0
	v_mov_b32_e32 v27, v0
	v_mov_b32_e32 v28, v0
	v_mov_b32_e32 v29, v0
	v_mov_b32_e32 v30, v0
	v_mov_b32_e32 v31, v0
	v_mov_b32_e32 v40, v0
	v_mov_b32_e32 v41, v0
	v_mov_b32_e32 v42, v0
	v_mov_b32_e32 v43, v0
	v_mov_b32_e32 v44, v0
	v_mov_b32_e32 v45, v0
	v_mov_b32_e32 v46, v0
	v_mov_b32_e32 v47, v0
	v_mov_b32_e32 v56, v0
	v_mov_b32_e32 v57, v0
	v_mov_b32_e32 v58, v0
	v_mov_b32_e32 v59, v0
	v_mov_b32_e32 v60, v0
	v_mov_b32_e32 v61, v0
	v_mov_b32_e32 v62, v0
	v_mov_b32_e32 v63, v0
	v_mov_b32_e32 v64, v0
	v_mov_b32_e32 v65, v0
	v_mov_b32_e32 v66, v0
	v_mov_b32_e32 v67, v0
	v_mov_b32_e32 v68, v0
	v_mov_b32_e32 v69, v0
	v_mov_b32_e32 v70, v0
	v_mov_b32_e32 v71, v0
	v_mov_b32_e32 v80, v0
	v_mov_b32_e32 v81, v0
	v_mov_b32_e32 v82, v0
	v_mov_b32_e32 v83, v0
	v_mov_b32_e32 v84, v0
	v_mov_b32_e32 v85, v0
	v_mov_b32_e32 v86, v0
	v_mov_b32_e32 v87, v0
	v_mov_b32_e32 v96, v0
	v_mov_b32_e32 v97, v0
	v_mov_b32_e32 v98, v0
	v_mov_b32_e32 v99, v0
	v_mov_b32_e32 v100, v0
	v_mov_b32_e32 v101, v0
	v_mov_b32_e32 v102, v0
	v_mov_b32_e32 v103, v0
	v_mov_b32_e32 v112, v0
	v_mov_b32_e32 v113, v0
	v_mov_b32_e32 v114, v0
	v_mov_b32_e32 v115, v0
	v_mov_b32_e32 v116, v0
	v_mov_b32_e32 v117, v0
	v_mov_b32_e32 v118, v0
	v_mov_b32_e32 v119, v0
	v_mov_b32_e32 v72, v0
	v_mov_b32_e32 v73, v0
	v_mov_b32_e32 v74, v0
	v_mov_b32_e32 v75, v0
	v_mov_b32_e32 v76, v0
	v_mov_b32_e32 v77, v0
	v_mov_b32_e32 v78, v0
	v_mov_b32_e32 v79, v0
	v_mov_b32_e32 v88, v0
	v_mov_b32_e32 v89, v0
	v_mov_b32_e32 v90, v0
	v_mov_b32_e32 v91, v0
	v_mov_b32_e32 v92, v0
	v_mov_b32_e32 v93, v0
	v_mov_b32_e32 v94, v0
	v_mov_b32_e32 v95, v0
	v_mov_b32_e32 v104, v0
	v_mov_b32_e32 v105, v0
	v_mov_b32_e32 v106, v0
	v_mov_b32_e32 v107, v0
	v_mov_b32_e32 v108, v0
	v_mov_b32_e32 v109, v0
	v_mov_b32_e32 v110, v0
	v_mov_b32_e32 v111, v0
	v_mov_b32_e32 v120, v0
	v_mov_b32_e32 v121, v0
	v_mov_b32_e32 v122, v0
	v_mov_b32_e32 v123, v0
	v_mov_b32_e32 v124, v0
	v_mov_b32_e32 v125, v0
	v_mov_b32_e32 v126, v0
	v_mov_b32_e32 v127, v0
	s_andn2_b64 vcc, exec, s[0:1]
	s_cbranch_vccnz .LBB0_653
